# attention prologue: bias-table loads issued before the Q loads, their wait and LDS writes moved after the Q loads; the lane-masked eighth load merged into the same group
# baseline (speedup 1.0000x reference)
; __device__ __forceinline__ void attn_unit(int u, const bf16_t* QB, const bf16_t* KB, const bf16_t* VTL, const bf16_t* VTC, const float* rpb, bf16_t* MIX, LAS float* rl, int lane) {
;     ...
;     for (int i = lane; i < 465; i += 64) { const int ro = i / 31, co = i - ro * 31; rl[ro * 32 + co] = rpb[h * 465 + i]; }
.LBB0_682:
	v_bfe_u32 v2, v181, 6, 3
	v_mul_u32_u24_e32 v0, 0x1d1, v2
	v_readlane_b32 s52, v253, 0
	v_add_lshl_u32 v0, v178, v0, 2
	v_readlane_b32 s64, v253, 12
	v_readlane_b32 s65, v253, 13
	v_readlane_b32 s53, v253, 1
	v_readlane_b32 s54, v253, 2
	v_readlane_b32 s55, v253, 3
	v_readlane_b32 s56, v253, 4
	v_readlane_b32 s57, v253, 5
	global_load_dword v239, v0, s[64:65]
	global_load_dword v240, v0, s[64:65] offset:256
	global_load_dword v241, v0, s[64:65] offset:512
	global_load_dword v242, v0, s[64:65] offset:768
	global_load_dword v243, v0, s[64:65] offset:1024
	global_load_dword v244, v0, s[64:65] offset:1280
	global_load_dword v245, v0, s[64:65] offset:1536
	v_readlane_b32 s58, v253, 6
	v_readlane_b32 s59, v253, 7
	v_readlane_b32 s60, v253, 8
	v_readlane_b32 s61, v253, 9
	v_readlane_b32 s62, v253, 10
	v_readlane_b32 s63, v253, 11
	v_readlane_b32 s66, v253, 14
	v_readlane_b32 s67, v253, 15
	s_mov_b64 s[98:99], exec
	v_readlane_b32 s100, v252, 29
	v_readlane_b32 s101, v252, 30
	s_and_b64 s[100:101], s[98:99], s[100:101]
	s_mov_b64 exec, s[100:101]
	s_cbranch_execz .Lrpb8_skip
	global_load_dword v246, v0, s[64:65] offset:1792
.Lrpb8_skip:
	s_mov_b64 exec, s[98:99]
; #define LAS __attribute__((address_space(3)))
; #define ATT_LOAD(kf, vf, kp, vp, vs) do { kf[0] = *(const bf16x8*)(kp); kf[1] = *(const bf16x8*)((kp) + 32); kf[2] = *(const bf16x8*)((kp) + 4 * 512); kf[3] = *(const bf16x8*)((kp) + 4 * 512 + 32); \
;         _Pragma("unroll") for (int dt = 0; dt < 4; ++dt) vf[dt] = *(const bf16x8*)((vp) + (size_t)dt * (vs)); } while (0)
; __device__ __forceinline__ void attn_unit(int u, const bf16_t* QB, const bf16_t* KB, const bf16_t* VTL, const bf16_t* VTC, const float* rpb, bf16_t* MIX, LAS float* rl, int lane) {
;     ...
;     for (int i = lane; i < 465; i += 64) { const int ro = i / 31, co = i - ro * 31; rl[ro * 32 + co] = rpb[h * 465 + i]; }
;     asm volatile("s_waitcnt lgkmcnt(0)" ::: "memory");
;     AttnState st[4];
;     LAS bf16x8* qs = (LAS bf16x8*)(rl + 512) + lane;
; #pragma unroll
;     for (int qb = 0; qb < 4; ++qb) { st[qb].m = -1e30f; st[qb].l = 0.f;
; #pragma unroll
;         for (int dt = 0; dt < 4; ++dt) st[qb].o[dt] = (f32x4){0.f, 0.f, 0.f, 0.f};
;         const size_t tq = (size_t)b * SEQ + r * 64 + 16 * qb + qi;
;         qs[(qb * 2 + 0) * 64] = *(const bf16x8*)(QB + tq * 512 + h * 64 + 8 * g); qs[(qb * 2 + 1) * 64] = *(const bf16x8*)(QB + tq * 512 + h * 64 + 32 + 8 * g); }
;     asm volatile("s_waitcnt lgkmcnt(0)" ::: "memory");
;     const int kap = 8 * (qi >> 2) + (qi & 3);
;     const bf16_t* vtl = VTL + ((size_t)(b * 8 + h) * 64 + qi) * 4096 + 8 * g;
;     const bf16_t* vtc = VTC + ((size_t)(b * 8 + h) * 64 + qi) * 256 + 8 * g;
;     const bf16_t* kl = KB + ((size_t)b * SEQ + kap) * 512 + h * 64 + 8 * g;
;     const bf16_t* kc = KB + ((size_t)NTOK + b * 256 + kap) * 512 + h * 64 + 8 * g;
;     ...
;     bf16x8 kA[4], vA[4], kB[4], vB[4];
;     ATT_LOAD(kA, vA, kl + (size_t)(rs * 64) * 512, vtl + rs * 64, 16 * 4096);
.LBB0_684:
	v_ashrrev_i32_e32 v36, 9, v181
	v_and_b32_e32 v3, 63, v181
	v_ashrrev_i32_e32 v37, 31, v36
	v_lshlrev_b64 v[160:161], 12, v[36:37]
	v_lshlrev_b32_e32 v198, 6, v3
	v_readlane_b32 s44, v253, 55
	v_or3_b32 v162, v140, v198, v160
	v_mov_b32_e32 v163, v161
	v_lshlrev_b32_e32 v0, 7, v2
	v_readlane_b32 s45, v253, 56
	v_lshlrev_b64 v[6:7], 10, v[162:163]
	v_mov_b32_e32 v157, v1
	v_lshl_add_u64 v[4:5], s[44:45], 0, v[0:1]
	v_lshl_add_u64 v[4:5], v[4:5], 0, v[6:7]
	v_lshl_add_u64 v[28:29], v[4:5], 0, v[156:157]
	s_movk_i32 s44, 0x4000
	v_add_co_u32_e32 v16, vcc, s44, v28
	s_mov_b32 s44, 0x8000
	s_nop 0
	v_addc_co_u32_e32 v17, vcc, 0, v29, vcc
	v_add_co_u32_e32 v24, vcc, s44, v28
	s_mov_b32 s44, 0xc000
	s_nop 0
	v_addc_co_u32_e32 v25, vcc, 0, v29, vcc
	v_add_co_u32_e32 v32, vcc, s44, v28
	s_waitcnt lgkmcnt(0)
	global_load_dwordx4 v[4:7], v[28:29], off
	global_load_dwordx4 v[8:11], v[28:29], off offset:64
	v_addc_co_u32_e32 v33, vcc, 0, v29, vcc
	global_load_dwordx4 v[12:15], v[16:17], off
	s_nop 0
	global_load_dwordx4 v[16:19], v[16:17], off offset:64
	s_nop 0
	global_load_dwordx4 v[20:23], v[24:25], off
	s_nop 0
	global_load_dwordx4 v[24:27], v[24:25], off offset:64
	s_nop 0
	global_load_dwordx4 v[28:31], v[32:33], off
	s_nop 0
	global_load_dwordx4 v[32:35], v[32:33], off offset:64
	s_waitcnt vmcnt(8)
	ds_write_b32 v165, v239 offset:40960
	ds_write_b32 v179, v240 offset:41216
	ds_write_b32 v188, v241 offset:41472
	ds_write_b32 v189, v242 offset:41728
	ds_write_b32 v190, v243 offset:41984
	ds_write_b32 v191, v244 offset:42240
	ds_write_b32 v192, v245 offset:42496
	s_mov_b64 s[98:99], exec
	v_readlane_b32 s100, v252, 29
	v_readlane_b32 s101, v252, 30
	s_and_b64 s[100:101], s[98:99], s[100:101]
	s_mov_b64 exec, s[100:101]
	ds_write_b32 v193, v246 offset:42752
	s_mov_b64 exec, s[98:99]
	v_lshlrev_b32_e32 v166, 8, v36
	v_lshlrev_b32_e32 v54, 3, v36
	v_add_u32_e32 v42, 0x4000, v166
	v_or_b32_e32 v40, v160, v142
	v_mov_b32_e32 v41, v161
	v_readlane_b32 s44, v253, 57
	v_or_b32_e32 v38, v54, v2
	v_ashrrev_i32_e32 v43, 31, v42
	v_or_b32_e32 v42, v42, v142
	v_lshlrev_b64 v[40:41], 10, v[40:41]
	v_readlane_b32 s45, v253, 58
	v_sub_u32_e64 v3, v3, 4 clamp
	v_ashrrev_i32_e32 v39, 31, v38
	v_lshlrev_b64 v[42:43], 10, v[42:43]
	v_lshl_add_u64 v[40:41], s[44:45], 0, v[40:41]
	v_min_u32_e32 v3, 56, v3
	v_lshlrev_b64 v[38:39], 6, v[38:39]
	v_lshl_add_u64 v[42:43], s[44:45], 0, v[42:43]
	v_lshl_add_u64 v[40:41], v[40:41], 0, v[0:1]
	v_or_b32_e32 v38, v38, v140
	v_lshl_add_u64 v[42:43], v[42:43], 0, v[0:1]
	v_lshlrev_b32_e32 v0, 16, v3
	v_lshl_add_u64 v[40:41], v[40:41], 0, v[156:157]
	v_lshlrev_b64 v[44:45], 13, v[38:39]
	v_lshl_add_u64 v[40:41], v[40:41], 0, v[0:1]
	s_movk_i32 s44, 0x1000
	v_lshl_add_u64 v[44:45], v[144:145], 0, v[44:45]
	v_lshlrev_b32_e32 v0, 7, v3
	v_add_co_u32_e32 v46, vcc, s44, v40
	v_lshl_add_u64 v[44:45], v[44:45], 0, v[0:1]
	s_nop 0
	v_addc_co_u32_e32 v47, vcc, 0, v41, vcc
	s_mov_b32 s44, 0x20000
	v_add_co_u32_e32 v48, vcc, s44, v44
	s_mov_b32 s44, 0x40000
	s_nop 0
	v_addc_co_u32_e32 v49, vcc, 0, v45, vcc
	v_add_co_u32_e32 v50, vcc, s44, v44
	s_mov_b32 s44, 0x60000
	s_nop 0
	v_addc_co_u32_e32 v51, vcc, 0, v45, vcc
	v_add_co_u32_e32 v52, vcc, s44, v44
	v_and_b32_e32 v3, 63, v194
	s_nop 0
	v_addc_co_u32_e32 v53, vcc, 0, v45, vcc
	v_lshrrev_b32_e32 v0, 6, v181
	v_and_b32_e32 v0, 7, v0
	v_lshlrev_b32_e32 v164, 6, v2
	v_lshlrev_b32_e32 v168, 7, v0
	v_or_b32_e32 v174, v54, v0
	v_ashrrev_i32_e32 v175, 31, v174
	v_lshl_add_u64 v[172:173], v[42:43], 0, v[156:157]
	v_mov_b32_e32 v0, v1
	v_readlane_b32 s52, v252, 33
	s_waitcnt vmcnt(7)
	ds_write_b128 v141, v[4:7] offset:43008
	s_waitcnt vmcnt(6)
	ds_write_b128 v141, v[8:11] offset:44032
	s_waitcnt vmcnt(5)
	ds_write_b128 v141, v[12:15] offset:45056
	s_waitcnt vmcnt(4)
	ds_write_b128 v141, v[16:19] offset:46080
	s_waitcnt vmcnt(3)
	ds_write_b128 v141, v[20:23] offset:47104
	s_waitcnt vmcnt(2)
	ds_write_b128 v141, v[24:27] offset:48128
	s_waitcnt vmcnt(1)
	ds_write_b128 v141, v[28:31] offset:49152
	s_waitcnt vmcnt(0)
	ds_write_b128 v141, v[32:35] offset:50176
	s_waitcnt lgkmcnt(0)
	global_load_dwordx4 v[20:23], v[40:41], off
	global_load_dwordx4 v[24:27], v[40:41], off offset:64
	global_load_dwordx4 v[28:31], v[46:47], off
	global_load_dwordx4 v[32:35], v[46:47], off offset:64
	global_load_dwordx4 v[8:11], v[44:45], off
	global_load_dwordx4 v[4:7], v[48:49], off
	global_load_dwordx4 v[12:15], v[50:51], off
	global_load_dwordx4 v[16:19], v[52:53], off
	v_sub_u32_e64 v40, v3, 4 clamp
	v_cmp_gt_u32_e32 vcc, 56, v40
	v_lshlrev_b32_e32 v3, 7, v3
	s_mov_b32 s50, 0
	v_cndmask_b32_e32 v41, 56, v40, vcc
	v_min_u32_e32 v40, 56, v40
	v_lshlrev_b32_e32 v40, 7, v40
	v_sub_u32_e32 v3, v40, v3
	v_add_u32_e32 v167, v195, v3
	v_add_u32_e32 v169, v196, v3
	v_add_u32_e32 v204, v197, v3
	v_lshlrev_b64 v[2:3], 9, v[38:39]
	v_lshlrev_b32_e32 v44, 16, v41
	v_lshl_add_u64 v[170:171], v[146:147], 0, v[2:3]
	v_lshlrev_b64 v[2:3], 22, v[36:37]
	v_or3_b32 v2, v2, v44, v168
	v_lshl_add_u64 v[182:183], v[150:151], 0, v[2:3]
	v_lshlrev_b64 v[2:3], 19, v[174:175]
	v_lshl_or_b32 v2, v41, 7, v2
	v_lshl_add_u64 v[184:185], v[152:153], 0, v[2:3]
	v_mov_b32_e32 v2, v1
	v_mov_b32_e32 v3, v1
	v_mov_b64_e32 v[50:51], v[2:3]
	v_mov_b64_e32 v[70:71], v[2:3]
	v_mov_b64_e32 v[74:75], v[2:3]
	v_mov_b64_e32 v[78:79], v[2:3]
	v_mov_b64_e32 v[82:83], v[2:3]
	v_mov_b64_e32 v[46:47], v[2:3]
	v_mov_b64_e32 v[86:87], v[2:3]
	v_mov_b64_e32 v[90:91], v[2:3]
	v_mov_b64_e32 v[94:95], v[2:3]
	v_mov_b64_e32 v[98:99], v[2:3]
	v_mov_b64_e32 v[42:43], v[2:3]
	v_mov_b64_e32 v[54:55], v[2:3]
	v_mov_b64_e32 v[58:59], v[2:3]
	v_mov_b64_e32 v[62:63], v[2:3]
	v_mov_b64_e32 v[66:67], v[2:3]
	v_mov_b64_e32 v[38:39], v[2:3]
	v_mov_b32_e32 v159, 0xf149f2ca
	v_mov_b32_e32 v157, 0
	v_mov_b64_e32 v[48:49], v[0:1]
	v_mov_b64_e32 v[68:69], v[0:1]
	v_mov_b64_e32 v[72:73], v[0:1]
	v_mov_b64_e32 v[76:77], v[0:1]
	v_mov_b64_e32 v[80:81], v[0:1]
	v_mov_b64_e32 v[44:45], v[0:1]
	v_mov_b32_e32 v201, 0
	v_mov_b32_e32 v199, 0xf149f2ca
	v_mov_b64_e32 v[84:85], v[0:1]
	v_mov_b64_e32 v[88:89], v[0:1]
	v_mov_b64_e32 v[92:93], v[0:1]
	v_mov_b64_e32 v[96:97], v[0:1]
	v_mov_b64_e32 v[40:41], v[0:1]
	v_mov_b32_e32 v203, 0
	v_mov_b32_e32 v200, 0xf149f2ca
	v_mov_b64_e32 v[52:53], v[0:1]
	v_mov_b64_e32 v[56:57], v[0:1]
	v_mov_b64_e32 v[60:61], v[0:1]
	v_mov_b64_e32 v[64:65], v[0:1]
	v_mov_b64_e32 v[36:37], v[0:1]
	v_mov_b32_e32 v202, 0
	v_mov_b32_e32 v0, 0xf149f2ca
	v_readlane_b32 s53, v252, 34
	s_branch .LBB0_686
